# v50 + first counted wait of each unit's peeled K-iteration leaves the epilogue stores in flight (vmcnt(6+stores)) in P2/P5/P12; equalising never-read loads behind the prologue
# baseline (speedup 1.0000x reference)
.LBB0_3264:
	s_ashr_i32 s11, s10, 31
	v_cmp_lt_i64_e32 vcc, s[12:13], v[162:163]
	s_lshl_b64 s[12:13], s[10:11], 19
	s_add_u32 s12, s36, s12
	s_addc_u32 s13, s37, s13
	s_and_b64 s[14:15], vcc, exec
	s_cselect_b32 s11, s13, s25
	s_cselect_b32 s57, s12, s24
	s_ashr_i32 s9, s8, 31
	s_lshl_b64 s[14:15], s[8:9], 19
	s_add_u32 s14, s38, s14
	s_addc_u32 s15, s39, s15
	s_and_b64 s[18:19], vcc, exec
	s_cselect_b32 s9, s15, s35
	s_cselect_b32 s60, s14, s34
	s_add_u32 s24, s24, 0x40080
	s_addc_u32 s25, s25, 0
	s_add_u32 s61, s34, 0x100
	s_addc_u32 s62, s35, 0
	s_mov_b32 s63, -2
	ds_read_b128 v[130:133], v171
	ds_read_b128 v[134:137], v171 offset:1024
	ds_read_b128 v[138:141], v171 offset:2048
	ds_read_b128 v[142:145], v171 offset:3072
	s_add_u32 s18, s24, 0xfffc0080
	s_addc_u32 s19, s25, -1
	s_cmp_eq_u32 s63, 12
	s_cselect_b32 s19, s11, s19
	s_cselect_b32 s18, s57, s18
	s_cselect_b32 s35, s9, s62
	s_cselect_b32 s34, s60, s61
	v_lshl_add_u64 v[174:175], s[24:25], 0, v[158:159]
	s_add_i32 m0, s43, 0xc000
	ds_read_b128 v[166:169], v173
	ds_read_b128 v[178:181], v173 offset:1024
	ds_read_b128 v[182:185], v173 offset:2048
	ds_read_b128 v[186:189], v173 offset:3072
	ds_read_b128 v[190:193], v173 offset:4096
	ds_read_b128 v[194:197], v173 offset:5120
	ds_read_b128 v[198:201], v173 offset:6144
	ds_read_b128 v[202:205], v173 offset:7168
	global_load_lds_dwordx4 v[174:175], off
	v_lshl_add_u64 v[174:175], s[24:25], 0, v[160:161]
	s_add_i32 m0, s43, 0xe000
	s_nop 0
	global_load_lds_dwordx4 v[174:175], off
	ds_read_b128 v[206:209], v177
	ds_read_b128 v[210:213], v177 offset:1024
	ds_read_b128 v[214:217], v177 offset:2048
	ds_read_b128 v[218:221], v177 offset:3072
	s_waitcnt lgkmcnt(0)
	s_setprio 1
	s_barrier
	v_mfma_f32_16x16x32_bf16 v[126:129], v[130:133], v[166:169], 0
	v_mfma_f32_16x16x32_bf16 v[122:125], v[138:141], v[166:169], 0
	v_mfma_f32_16x16x32_bf16 v[110:113], v[130:133], v[182:185], 0
	v_mfma_f32_16x16x32_bf16 v[106:109], v[138:141], v[182:185], 0
	v_mfma_f32_16x16x32_bf16 v[94:97], v[130:133], v[190:193], 0
	v_mfma_f32_16x16x32_bf16 v[90:93], v[138:141], v[190:193], 0
	v_mfma_f32_16x16x32_bf16 v[78:81], v[130:133], v[198:201], 0
	v_mfma_f32_16x16x32_bf16 v[74:77], v[138:141], v[198:201], 0
	v_mfma_f32_16x16x32_bf16 v[126:129], v[134:137], v[178:181], v[126:129]
	v_mfma_f32_16x16x32_bf16 v[122:125], v[142:145], v[178:181], v[122:125]
	v_mfma_f32_16x16x32_bf16 v[110:113], v[134:137], v[186:189], v[110:113]
	v_mfma_f32_16x16x32_bf16 v[106:109], v[142:145], v[186:189], v[106:109]
	v_mfma_f32_16x16x32_bf16 v[94:97], v[134:137], v[194:197], v[94:97]
	v_mfma_f32_16x16x32_bf16 v[90:93], v[142:145], v[194:197], v[90:93]
	v_mfma_f32_16x16x32_bf16 v[78:81], v[134:137], v[202:205], v[78:81]
	v_mfma_f32_16x16x32_bf16 v[74:77], v[142:145], v[202:205], v[74:77]
	v_mfma_f32_16x16x32_bf16 v[118:121], v[206:209], v[166:169], 0
	v_mfma_f32_16x16x32_bf16 v[114:117], v[214:217], v[166:169], 0
	v_mfma_f32_16x16x32_bf16 v[102:105], v[206:209], v[182:185], 0
	v_mfma_f32_16x16x32_bf16 v[98:101], v[214:217], v[182:185], 0
	v_mfma_f32_16x16x32_bf16 v[86:89], v[206:209], v[190:193], 0
	v_mfma_f32_16x16x32_bf16 v[82:85], v[214:217], v[190:193], 0
	v_mfma_f32_16x16x32_bf16 v[70:73], v[206:209], v[198:201], 0
	v_mfma_f32_16x16x32_bf16 v[66:69], v[214:217], v[198:201], 0
	v_mfma_f32_16x16x32_bf16 v[118:121], v[210:213], v[178:181], v[118:121]
	v_mfma_f32_16x16x32_bf16 v[114:117], v[218:221], v[178:181], v[114:117]
	v_mfma_f32_16x16x32_bf16 v[102:105], v[210:213], v[186:189], v[102:105]
	v_mfma_f32_16x16x32_bf16 v[98:101], v[218:221], v[186:189], v[98:101]
	v_mfma_f32_16x16x32_bf16 v[86:89], v[210:213], v[194:197], v[86:89]
	v_mfma_f32_16x16x32_bf16 v[82:85], v[218:221], v[194:197], v[82:85]
	v_mfma_f32_16x16x32_bf16 v[70:73], v[210:213], v[202:205], v[70:73]
	v_mfma_f32_16x16x32_bf16 v[66:69], v[218:221], v[202:205], v[66:69]
	s_barrier
	s_setprio 0
	s_add_i32 s20, s54, s42
	v_lshl_add_u64 v[174:175], s[34:35], 0, v[150:151]
	s_mov_b32 m0, s20
	s_nop 0
	global_load_lds_dwordx4 v[174:175], off
	v_lshl_add_u64 v[222:223], s[34:35], 0, v[146:147]
	s_add_i32 m0, s20, 0x2000
	s_nop 0
	global_load_lds_dwordx4 v[222:223], off
	s_mov_b32 m0, s43
	v_lshl_add_u64 v[224:225], s[18:19], 0, v[152:153]
	ds_read_b128 v[166:169], v173 offset:16384
	ds_read_b128 v[178:181], v173 offset:17408
	ds_read_b128 v[182:185], v173 offset:18432
	ds_read_b128 v[186:189], v173 offset:19456
	ds_read_b128 v[190:193], v173 offset:20480
	ds_read_b128 v[194:197], v173 offset:21504
	ds_read_b128 v[198:201], v173 offset:22528
	ds_read_b128 v[202:205], v173 offset:23552
	global_load_lds_dwordx4 v[224:225], off
	v_lshl_add_u64 v[226:227], s[18:19], 0, v[148:149]
	s_mov_b32 m0, s44
	s_nop 0
	global_load_lds_dwordx4 v[226:227], off
	s_waitcnt vmcnt(14)
	s_waitcnt lgkmcnt(0)
	s_setprio 1
	s_barrier
	v_mfma_f32_16x16x32_bf16 v[62:65], v[130:133], v[166:169], 0
	v_mfma_f32_16x16x32_bf16 v[58:61], v[138:141], v[166:169], 0
	v_mfma_f32_16x16x32_bf16 v[46:49], v[130:133], v[182:185], 0
	v_mfma_f32_16x16x32_bf16 v[42:45], v[138:141], v[182:185], 0
	v_mfma_f32_16x16x32_bf16 v[30:33], v[130:133], v[190:193], 0
	v_mfma_f32_16x16x32_bf16 v[26:29], v[138:141], v[190:193], 0
	v_mfma_f32_16x16x32_bf16 v[14:17], v[130:133], v[198:201], 0
	v_mfma_f32_16x16x32_bf16 v[10:13], v[138:141], v[198:201], 0
	v_mfma_f32_16x16x32_bf16 v[62:65], v[134:137], v[178:181], v[62:65]
	v_mfma_f32_16x16x32_bf16 v[58:61], v[142:145], v[178:181], v[58:61]
	v_mfma_f32_16x16x32_bf16 v[46:49], v[134:137], v[186:189], v[46:49]
	v_mfma_f32_16x16x32_bf16 v[42:45], v[142:145], v[186:189], v[42:45]
	v_mfma_f32_16x16x32_bf16 v[30:33], v[134:137], v[194:197], v[30:33]
	v_mfma_f32_16x16x32_bf16 v[26:29], v[142:145], v[194:197], v[26:29]
	v_mfma_f32_16x16x32_bf16 v[14:17], v[134:137], v[202:205], v[14:17]
	v_mfma_f32_16x16x32_bf16 v[10:13], v[142:145], v[202:205], v[10:13]
	v_mfma_f32_16x16x32_bf16 v[54:57], v[206:209], v[166:169], 0
	v_mfma_f32_16x16x32_bf16 v[50:53], v[214:217], v[166:169], 0
	v_mfma_f32_16x16x32_bf16 v[38:41], v[206:209], v[182:185], 0
	v_mfma_f32_16x16x32_bf16 v[34:37], v[214:217], v[182:185], 0
	v_mfma_f32_16x16x32_bf16 v[22:25], v[206:209], v[190:193], 0
	v_mfma_f32_16x16x32_bf16 v[18:21], v[214:217], v[190:193], 0
	v_mfma_f32_16x16x32_bf16 v[6:9], v[206:209], v[198:201], 0
	v_mfma_f32_16x16x32_bf16 v[2:5], v[214:217], v[198:201], 0
	v_mfma_f32_16x16x32_bf16 v[54:57], v[210:213], v[178:181], v[54:57]
	v_mfma_f32_16x16x32_bf16 v[50:53], v[218:221], v[178:181], v[50:53]
	v_mfma_f32_16x16x32_bf16 v[38:41], v[210:213], v[186:189], v[38:41]
	v_mfma_f32_16x16x32_bf16 v[34:37], v[218:221], v[186:189], v[34:37]
	v_mfma_f32_16x16x32_bf16 v[22:25], v[210:213], v[194:197], v[22:25]
	v_mfma_f32_16x16x32_bf16 v[18:21], v[218:221], v[194:197], v[18:21]
	v_mfma_f32_16x16x32_bf16 v[6:9], v[210:213], v[202:205], v[6:9]
	v_mfma_f32_16x16x32_bf16 v[2:5], v[218:221], v[202:205], v[2:5]
	s_barrier
	s_setprio 0
	s_add_u32 s20, s34, 0x40000
	s_addc_u32 s21, s35, 0
	s_add_i32 s64, s55, s42
	v_lshl_add_u64 v[252:253], s[20:21], 0, v[150:151]
	s_mov_b32 m0, s64
	s_nop 0
	global_load_lds_dwordx4 v[252:253], off
	v_lshl_add_u64 v[252:253], s[20:21], 0, v[146:147]
	s_add_i32 m0, s64, 0x2000
	s_nop 0
	global_load_lds_dwordx4 v[252:253], off
	s_add_i32 s20, 0, 0x18000
	v_add_u32_e32 v142, s20, v157
	ds_read_b128 v[130:133], v142
	ds_read_b128 v[134:137], v142 offset:1024
	ds_read_b128 v[138:141], v142 offset:2048
	ds_read_b128 v[142:145], v142 offset:3072
	s_add_u32 s18, s18, 0x40000
	s_addc_u32 s19, s19, 0
	s_mov_b32 m0, s45
	v_lshl_add_u64 v[206:207], s[18:19], 0, v[152:153]
	ds_read_b128 v[166:169], v173 offset:32768
	ds_read_b128 v[178:181], v173 offset:33792
	ds_read_b128 v[182:185], v173 offset:34816
	ds_read_b128 v[186:189], v173 offset:35840
	ds_read_b128 v[190:193], v173 offset:36864
	ds_read_b128 v[194:197], v173 offset:37888
	ds_read_b128 v[198:201], v173 offset:38912
	ds_read_b128 v[202:205], v173 offset:39936
	global_load_lds_dwordx4 v[206:207], off
	v_lshl_add_u64 v[206:207], s[18:19], 0, v[148:149]
	s_mov_b32 m0, s46
	s_nop 0
	global_load_lds_dwordx4 v[206:207], off
	s_add_i32 s21, 0, 0x1c000
	v_add_u32_e32 v154, s21, v157
	ds_read_b128 v[206:209], v154
	ds_read_b128 v[210:213], v154 offset:1024
	ds_read_b128 v[214:217], v154 offset:2048
	ds_read_b128 v[218:221], v154 offset:3072
	s_waitcnt vmcnt(8)
	s_waitcnt lgkmcnt(0)
	s_setprio 1
	s_barrier
	v_mfma_f32_16x16x32_bf16 v[126:129], v[130:133], v[166:169], v[126:129]
	v_mfma_f32_16x16x32_bf16 v[122:125], v[138:141], v[166:169], v[122:125]
	v_mfma_f32_16x16x32_bf16 v[110:113], v[130:133], v[182:185], v[110:113]
	v_mfma_f32_16x16x32_bf16 v[106:109], v[138:141], v[182:185], v[106:109]
	v_mfma_f32_16x16x32_bf16 v[94:97], v[130:133], v[190:193], v[94:97]
	v_mfma_f32_16x16x32_bf16 v[90:93], v[138:141], v[190:193], v[90:93]
	v_mfma_f32_16x16x32_bf16 v[78:81], v[130:133], v[198:201], v[78:81]
	v_mfma_f32_16x16x32_bf16 v[74:77], v[138:141], v[198:201], v[74:77]
	v_mfma_f32_16x16x32_bf16 v[126:129], v[134:137], v[178:181], v[126:129]
	v_mfma_f32_16x16x32_bf16 v[122:125], v[142:145], v[178:181], v[122:125]
	v_mfma_f32_16x16x32_bf16 v[110:113], v[134:137], v[186:189], v[110:113]
	v_mfma_f32_16x16x32_bf16 v[106:109], v[142:145], v[186:189], v[106:109]
	v_mfma_f32_16x16x32_bf16 v[94:97], v[134:137], v[194:197], v[94:97]
	v_mfma_f32_16x16x32_bf16 v[90:93], v[142:145], v[194:197], v[90:93]
	v_mfma_f32_16x16x32_bf16 v[78:81], v[134:137], v[202:205], v[78:81]
	v_mfma_f32_16x16x32_bf16 v[74:77], v[142:145], v[202:205], v[74:77]
	v_mfma_f32_16x16x32_bf16 v[118:121], v[206:209], v[166:169], v[118:121]
	v_mfma_f32_16x16x32_bf16 v[114:117], v[214:217], v[166:169], v[114:117]
	v_mfma_f32_16x16x32_bf16 v[102:105], v[206:209], v[182:185], v[102:105]
	v_mfma_f32_16x16x32_bf16 v[98:101], v[214:217], v[182:185], v[98:101]
	v_mfma_f32_16x16x32_bf16 v[86:89], v[206:209], v[190:193], v[86:89]
	v_mfma_f32_16x16x32_bf16 v[82:85], v[214:217], v[190:193], v[82:85]
	v_mfma_f32_16x16x32_bf16 v[70:73], v[206:209], v[198:201], v[70:73]
	v_mfma_f32_16x16x32_bf16 v[66:69], v[214:217], v[198:201], v[66:69]
	v_mfma_f32_16x16x32_bf16 v[118:121], v[210:213], v[178:181], v[118:121]
	v_mfma_f32_16x16x32_bf16 v[114:117], v[218:221], v[178:181], v[114:117]
	v_mfma_f32_16x16x32_bf16 v[102:105], v[210:213], v[186:189], v[102:105]
	v_mfma_f32_16x16x32_bf16 v[98:101], v[218:221], v[186:189], v[98:101]
	v_mfma_f32_16x16x32_bf16 v[86:89], v[210:213], v[194:197], v[86:89]
	v_mfma_f32_16x16x32_bf16 v[82:85], v[218:221], v[194:197], v[82:85]
	v_mfma_f32_16x16x32_bf16 v[70:73], v[210:213], v[202:205], v[70:73]
	v_mfma_f32_16x16x32_bf16 v[66:69], v[218:221], v[202:205], v[66:69]
	s_barrier
	s_setprio 0
	s_add_i32 s18, s20, s42
	v_lshl_add_u64 v[174:175], v[174:175], 0, s[6:7]
	s_mov_b32 m0, s18
	s_nop 0
	global_load_lds_dwordx4 v[174:175], off
	v_lshl_add_u64 v[174:175], v[222:223], 0, s[6:7]
	s_add_i32 m0, s18, 0x2000
	s_nop 0
	global_load_lds_dwordx4 v[174:175], off
	s_mov_b32 m0, s50
	v_lshl_add_u64 v[174:175], v[224:225], 0, s[6:7]
	ds_read_b128 v[166:169], v173 offset:49152
	ds_read_b128 v[178:181], v173 offset:50176
	ds_read_b128 v[182:185], v173 offset:51200
	ds_read_b128 v[186:189], v173 offset:52224
	ds_read_b128 v[190:193], v173 offset:53248
	ds_read_b128 v[194:197], v173 offset:54272
	ds_read_b128 v[198:201], v173 offset:55296
	ds_read_b128 v[202:205], v173 offset:56320
	global_load_lds_dwordx4 v[174:175], off
	v_lshl_add_u64 v[174:175], v[226:227], 0, s[6:7]
	s_mov_b32 m0, s51
	s_nop 0
	global_load_lds_dwordx4 v[174:175], off
	s_add_u32 s18, s34, 0x40080
	s_addc_u32 s19, s35, 0
	s_add_i32 s20, s21, s42
	v_lshl_add_u64 v[252:253], s[18:19], 0, v[150:151]
	s_mov_b32 m0, s20
	s_nop 0
	global_load_lds_dwordx4 v[252:253], off
	v_lshl_add_u64 v[252:253], s[18:19], 0, v[146:147]
	s_add_i32 m0, s20, 0x2000
	s_nop 0
	global_load_lds_dwordx4 v[252:253], off
	s_waitcnt vmcnt(6)
	s_waitcnt lgkmcnt(0)
	s_setprio 1
	s_barrier
	v_mfma_f32_16x16x32_bf16 v[62:65], v[130:133], v[166:169], v[62:65]
	v_mfma_f32_16x16x32_bf16 v[58:61], v[138:141], v[166:169], v[58:61]
	v_mfma_f32_16x16x32_bf16 v[46:49], v[130:133], v[182:185], v[46:49]
	v_mfma_f32_16x16x32_bf16 v[42:45], v[138:141], v[182:185], v[42:45]
	v_mfma_f32_16x16x32_bf16 v[30:33], v[130:133], v[190:193], v[30:33]
	v_mfma_f32_16x16x32_bf16 v[26:29], v[138:141], v[190:193], v[26:29]
	v_mfma_f32_16x16x32_bf16 v[14:17], v[130:133], v[198:201], v[14:17]
	v_mfma_f32_16x16x32_bf16 v[10:13], v[138:141], v[198:201], v[10:13]
	v_mfma_f32_16x16x32_bf16 v[62:65], v[134:137], v[178:181], v[62:65]
	v_mfma_f32_16x16x32_bf16 v[58:61], v[142:145], v[178:181], v[58:61]
	v_mfma_f32_16x16x32_bf16 v[46:49], v[134:137], v[186:189], v[46:49]
	v_mfma_f32_16x16x32_bf16 v[42:45], v[142:145], v[186:189], v[42:45]
	v_mfma_f32_16x16x32_bf16 v[30:33], v[134:137], v[194:197], v[30:33]
	v_mfma_f32_16x16x32_bf16 v[26:29], v[142:145], v[194:197], v[26:29]
	v_mfma_f32_16x16x32_bf16 v[14:17], v[134:137], v[202:205], v[14:17]
	v_mfma_f32_16x16x32_bf16 v[10:13], v[142:145], v[202:205], v[10:13]
	v_mfma_f32_16x16x32_bf16 v[54:57], v[206:209], v[166:169], v[54:57]
	v_mfma_f32_16x16x32_bf16 v[50:53], v[214:217], v[166:169], v[50:53]
	v_mfma_f32_16x16x32_bf16 v[38:41], v[206:209], v[182:185], v[38:41]
	v_mfma_f32_16x16x32_bf16 v[34:37], v[214:217], v[182:185], v[34:37]
	v_mfma_f32_16x16x32_bf16 v[22:25], v[206:209], v[190:193], v[22:25]
	v_mfma_f32_16x16x32_bf16 v[18:21], v[214:217], v[190:193], v[18:21]
	v_mfma_f32_16x16x32_bf16 v[6:9], v[206:209], v[198:201], v[6:9]
	v_mfma_f32_16x16x32_bf16 v[2:5], v[214:217], v[198:201], v[2:5]
	v_mfma_f32_16x16x32_bf16 v[54:57], v[210:213], v[178:181], v[54:57]
	v_mfma_f32_16x16x32_bf16 v[50:53], v[218:221], v[178:181], v[50:53]
	v_mfma_f32_16x16x32_bf16 v[38:41], v[210:213], v[186:189], v[38:41]
	v_mfma_f32_16x16x32_bf16 v[34:37], v[218:221], v[186:189], v[34:37]
	v_mfma_f32_16x16x32_bf16 v[22:25], v[210:213], v[194:197], v[22:25]
	v_mfma_f32_16x16x32_bf16 v[18:21], v[218:221], v[194:197], v[18:21]
	v_mfma_f32_16x16x32_bf16 v[6:9], v[210:213], v[202:205], v[6:9]
	v_mfma_f32_16x16x32_bf16 v[2:5], v[218:221], v[202:205], v[2:5]
	s_add_i32 s63, s63, 2
	s_add_u32 s24, s24, 0x100
	s_addc_u32 s25, s25, 0
	s_add_u32 s61, s61, 0x100
	s_addc_u32 s62, s62, 0
	s_cmp_gt_u32 s63, 13
